# v20 + grid barrier 4 removed: P5 GEMM (needs only barrier-3 data) starts right after P4; decode-combine WGs release+count, sample_outproj WGs run it after their GEMM unit behind a counter poll + acqui
# speedup vs baseline: 1.0599x; 1.0220x over previous
; #define PSTAMP0(i) do { if (PROBE_SEG >= 40 && blockIdx.x == 0 && threadIdx.x == 0) ((volatile LAS unsigned long long*)(ctlw + 32))[20 + (i)] = __builtin_amdgcn_s_memrealtime(); } while (0)
; #define STAMP() do { if (PROBE_SEG >= 0 && bx == 0 && tid == 0) { tst[nst] = __builtin_amdgcn_s_memrealtime(); } ++nst; } while (0)
; #define BOTH(k) (IN(k) && IN((k) + 1))
; __global__ void __launch_bounds__(512, 2) hymba_fwd(Params p) {
;     ...
;     if (IN(4)) { phase4(p, lds, ctlw, vcu, G, 0); if (BOTH(4)) GBAR(); STAMP(); }
;     if (IN(5)) {
;         pg8::Gemm g{(const bf16_t*)(p.ws + WS_MIX), (const bf16_t*)(p.ws + WS_WOUT), nullptr, nullptr, DM};
;         pg8::Order S; S.init(MP / 256, DM / 256, 0, 1, G, bx);
;         Epi5 E{p.in[I_XP], p.out, (const float*)(p.ws + WS_SSQ)};
;         PSTAMP0(4);
;         if (bx < 128) { sample_outproj(p, lds, bx); __syncthreads(); }
;         PSTAMP0(5);
;         pg8::gemm_phase<Epi5>(lds, g, S, E);
.LBB0_1074:
	s_cmp_eq_u32 s98, 4
	s_cbranch_scc0 .Lp4_do
	v_readlane_b32 s50, v254, 3
	v_readlane_b32 s51, v254, 4
	s_cmp_lt_i32 s51, 6
	s_cbranch_scc1 .Lp4_keepbar
	s_waitcnt vmcnt(0) lgkmcnt(0)
	s_barrier
	s_not_b32 s0, s95
	v_readlane_b32 s1, v254, 2
	s_add_i32 s0, s1, s0
	s_cmp_gt_i32 s0, 63
	s_cbranch_scc1 .LBB0_1184
	v_cmp_eq_u32_e32 vcc, 0, v0
	s_and_saveexec_b64 s[0:1], vcc
	s_cbranch_execz .Lp4_pubdone
	buffer_wbl2 sc1
	s_waitcnt vmcnt(0)
	v_mov_b32_e32 v1, 0xc00
	v_mov_b32_e32 v2, 1
	global_atomic_add v1, v2, s[90:91]
	s_waitcnt vmcnt(0)
.Lp4_pubdone:
	s_or_b64 exec, exec, s[0:1]
	s_branch .LBB0_1184
.Lp4_keepbar:
	v_cmp_eq_u32_e64 s[0:1], 0, v0
	s_branch .Lp4_after

; #define LAS __attribute__((address_space(3)))
; #define PSTAMP0(i) do { if (PROBE_SEG >= 40 && blockIdx.x == 0 && threadIdx.x == 0) ((volatile LAS unsigned long long*)(ctlw + 32))[20 + (i)] = __builtin_amdgcn_s_memrealtime(); } while (0)
; __device__ __forceinline__ void sample_outproj(const Params& p, LAS unsigned char* lds, int c) {
;     int tid = threadIdx.x; asm volatile("" : "+v"(tid));
;     const int wid = __builtin_amdgcn_readfirstlane(tid >> 6), lane = tid & 63, j16 = lane & 15, ig = lane >> 4;
;     const bf16_t* MIX = (const bf16_t*)(p.ws + WS_MIX) + (size_t)MP * 2048; const bf16_t* WT = (const bf16_t*)(p.ws + WS_WOUT) + (size_t)(16 * c) * 2048;
;     const float* SSQ = (const float*)(p.ws + WS_SSQ) + (size_t)MP * 8;
;     f32x4 acc[4];
; #pragma unroll
;     for (int rb = 0; rb < 4; ++rb) acc[rb] = f32x4{0.f, 0.f, 0.f, 0.f};
;     float xin[2];
; #pragma unroll
;     for (int i = 0; i < 2; ++i) { const int e = tid + 512 * i; xin[i] = p.in[I_XS][(size_t)(e >> 4) * DM + 16 * c + (e & 15)]; }
;     LAS float* rsl = (LAS float*)(lds + 32768);
;     f32x4 sq0 = f32x4{0.f, 0.f, 0.f, 0.f}, sq1 = sq0;
;     if (tid < 64) { sq0 = *(const f32x4*)(SSQ + tid * 8); sq1 = *(const f32x4*)(SSQ + tid * 8 + 4); }
;     bf16x8 bfr[8], afr[8][4];
; #pragma unroll
;     for (int ks = 0; ks < 8; ++ks) { const int k = 256 * wid + 32 * ks + 8 * ig;
;         bfr[ks] = *(const bf16x8*)(WT + (size_t)j16 * 2048 + k);
; #pragma unroll
;         for (int rb = 0; rb < 4; ++rb) afr[ks][rb] = *(const bf16x8*)(MIX + (size_t)(16 * rb + j16) * 2048 + k); }
; __global__ void __launch_bounds__(512, 2) hymba_fwd(Params p) {
;     ...
;     if (IN(5)) {
;         pg8::Gemm g{(const bf16_t*)(p.ws + WS_MIX), (const bf16_t*)(p.ws + WS_WOUT), nullptr, nullptr, DM};
;         pg8::Order S; S.init(MP / 256, DM / 256, 0, 1, G, bx);
;         Epi5 E{p.in[I_XP], p.out, (const float*)(p.ws + WS_SSQ)};
;         PSTAMP0(4);
;         if (bx < 128) { sample_outproj(p, lds, bx); __syncthreads(); }
;         PSTAMP0(5);
;         pg8::gemm_phase<Epi5>(lds, g, S, E);
.LBB0_1184:
	s_cmp_gt_i32 s50, 5
	s_cselect_b64 s[0:1], -1, 0
	s_cmp_lt_i32 s51, 6
	s_cselect_b64 s[2:3], -1, 0
	s_or_b64 s[0:1], s[0:1], s[2:3]
	s_and_b64 vcc, exec, s[0:1]
	s_cbranch_vccnz .LBB0_1219
	s_add_u32 s24, s90, 0x2600000
	s_addc_u32 s33, s91, 0
	v_mov_b32_e32 v255, v0
	s_cmp_eq_u32 s98, 4
	s_cbranch_scc1 .LBB0_1193
	s_cmpk_gt_i32 s95, 0x7f
	s_cbranch_scc1 .LBB0_1193
.Lp5_sample:
	s_lshl_b32 s4, s95, 4
	s_ashr_i32 s5, s4, 31
	s_waitcnt vmcnt(0)
	v_mov_b32_e32 v33, v0
	s_lshl_b64 s[2:3], s[4:5], 2
	v_mov_b32_e32 v11, 0
	v_and_b32_e32 v10, 15, v33
	s_add_u32 s0, s38, s2
	v_ashrrev_i32_e32 v4, 4, v33
	v_add_u32_e32 v32, 0x200, v33
	s_addc_u32 s1, s39, s3
	v_lshlrev_b32_e32 v26, 2, v10
	v_mov_b32_e32 v27, v11
	v_ashrrev_i32_e32 v5, 31, v4
	v_ashrrev_i32_e32 v6, 4, v32
	s_waitcnt lgkmcnt(0)
	v_lshl_add_u64 v[2:3], s[0:1], 0, v[26:27]
	v_lshlrev_b64 v[30:31], 13, v[4:5]
	v_ashrrev_i32_e32 v7, 31, v6
	v_lshl_add_u64 v[4:5], v[2:3], 0, v[30:31]
	v_lshlrev_b64 v[28:29], 13, v[6:7]
	v_lshl_add_u64 v[2:3], v[2:3], 0, v[28:29]
	global_load_dword v27, v[4:5], off
	global_load_dword v1, v[2:3], off
	v_readfirstlane_b32 s8, v33
	v_cmp_gt_i32_e64 s[0:1], 64, v33
	v_mov_b32_e32 v6, 0
	v_mov_b32_e32 v7, 0
	v_mov_b32_e32 v8, 0
	v_mov_b32_e32 v9, 0
	v_mov_b32_e32 v2, 0
	v_mov_b32_e32 v3, 0
	v_mov_b32_e32 v4, 0
	v_mov_b32_e32 v5, 0
	s_and_saveexec_b64 s[6:7], s[0:1]
	s_cbranch_execz .LBB0_1188
	v_lshlrev_b32_e32 v2, 3, v33
	v_ashrrev_i32_e32 v3, 31, v2
	v_lshl_add_u64 v[2:3], v[2:3], 2, s[90:91]
	v_add_co_u32_e32 v14, vcc, 0xdd40000, v2
	s_mov_b64 s[10:11], 0xdd40000
	s_nop 0
	v_addc_co_u32_e32 v15, vcc, 0, v3, vcc
	v_lshl_add_u64 v[12:13], v[2:3], 0, s[10:11]
	global_load_dwordx4 v[2:5], v[14:15], off
	global_load_dwordx4 v[6:9], v[12:13], off offset:16

; #define LAS __attribute__((address_space(3)))
; __device__ __forceinline__ void sample_outproj(const Params& p, LAS unsigned char* lds, int c) {
;     ...
;     LAS float* red = (LAS float*)lds;
; #pragma unroll
;     for (int rb = 0; rb < 4; ++rb)
; #pragma unroll
;         for (int r = 0; r < 4; ++r) red[(wid * 64 + 16 * rb + 4 * ig + r) * 16 + j16] = acc[rb][r];
;     __syncthreads();
; #pragma unroll
;     for (int i = 0; i < 2; ++i) { const int e = tid + 512 * i, row = e >> 4, col = e & 15; float v = 0.f;
; #pragma unroll
;         for (int w = 0; w < 8; ++w) v += red[(w * 64 + row) * 16 + col];
;         p.out[O_YS + (size_t)row * DM + 16 * c + col] = xin[i] + v; }
; }
.LBB0_1192:
	s_lshl_b32 s0, s8, 6
	v_add_u32_e32 v8, 0, v26
	v_lshlrev_b32_e32 v2, 8, v34
	s_and_b32 s0, s0, 0xfffff000
	v_add3_u32 v2, v8, v2, s0
	v_add_u32_e32 v3, 0x400, v2
	ds_write2_b32 v2, v18, v19 offset1:16
	ds_write2_b32 v2, v20, v21 offset0:32 offset1:48
	ds_write2_b32 v3, v22, v23 offset1:16
	ds_write2_b32 v3, v24, v25 offset0:32 offset1:48
	v_add_u32_e32 v3, 0x800, v2
	v_add_u32_e32 v2, 0xc00, v2
	ds_write2_b32 v3, v14, v15 offset1:16
	ds_write2_b32 v3, v16, v17 offset0:32 offset1:48
	ds_write2_b32 v2, v10, v11 offset1:16
	ds_write2_b32 v2, v12, v13 offset0:32 offset1:48
	v_and_b32_e32 v2, 0x3ffffff0, v33
	v_lshl_add_u32 v9, v2, 2, v8
	s_waitcnt lgkmcnt(0)
	s_barrier
	ds_read2st64_b32 v[2:3], v9 offset1:16
	ds_read2st64_b32 v[4:5], v9 offset0:32 offset1:48
	ds_read2st64_b32 v[6:7], v9 offset0:64 offset1:80
	s_brev_b32 s0, 32
	s_waitcnt lgkmcnt(2)
	v_add_f32_e32 v2, 0, v2
	v_add_f32_e32 v10, v2, v3
	ds_read2st64_b32 v[2:3], v9 offset0:96 offset1:112
	s_waitcnt lgkmcnt(2)
	v_add_f32_e32 v4, v10, v4
	v_add_f32_e32 v4, v4, v5
	s_waitcnt lgkmcnt(1)
	v_add_f32_e32 v4, v4, v6
	v_add_f32_e32 v4, v4, v7
	s_waitcnt lgkmcnt(0)
	v_add_f32_e32 v2, v4, v2
	v_add_f32_e32 v2, v2, v3
	v_add_f32_e32 v6, v27, v2
	v_lshl_add_u64 v[2:3], s[88:89], 0, v[30:31]
	v_lshl_add_u64 v[2:3], v[2:3], 0, s[2:3]
	v_mov_b32_e32 v27, 0
	v_and_b32_e32 v4, 0x3ffffff0, v32
	v_lshl_add_u64 v[2:3], v[2:3], 0, v[26:27]
	v_lshl_add_u32 v8, v4, 2, v8
	ds_read2st64_b32 v[4:5], v8 offset1:16
	v_add_co_u32_e32 v2, vcc, s0, v2
	s_waitcnt lgkmcnt(0)
	v_add_f32_e32 v4, 0, v4
	v_addc_co_u32_e32 v3, vcc, 0, v3, vcc
	global_store_dword v[2:3], v6, off
	ds_read2st64_b32 v[2:3], v8 offset0:32 offset1:48
	ds_read2st64_b32 v[6:7], v8 offset0:64 offset1:80
	v_add_f32_e32 v9, v4, v5
	ds_read2st64_b32 v[4:5], v8 offset0:96 offset1:112
	s_waitcnt lgkmcnt(2)
	v_add_f32_e32 v2, v9, v2
	v_add_f32_e32 v2, v2, v3
	s_waitcnt lgkmcnt(1)
	v_add_f32_e32 v2, v2, v6
	v_add_f32_e32 v2, v2, v7
	s_waitcnt lgkmcnt(0)
	v_add_f32_e32 v2, v2, v4
	v_add_f32_e32 v2, v2, v5
	v_add_f32_e32 v1, v1, v2
	v_lshl_add_u64 v[2:3], s[88:89], 0, v[28:29]
	v_lshl_add_u64 v[2:3], v[2:3], 0, s[2:3]
	v_lshl_add_u64 v[2:3], v[2:3], 0, v[26:27]
	v_add_co_u32_e32 v2, vcc, 0x4000000, v2
	s_nop 1
	v_addc_co_u32_e32 v3, vcc, 0, v3, vcc
	global_store_dword v[2:3], v1, off
	s_barrier
	s_cmp_eq_u32 s98, 5
	s_cbranch_scc1 .Lp5_exit

; #define PSTAMP0(i) do { if (PROBE_SEG >= 40 && blockIdx.x == 0 && threadIdx.x == 0) ((volatile LAS unsigned long long*)(ctlw + 32))[20 + (i)] = __builtin_amdgcn_s_memrealtime(); } while (0)
; __global__ void __launch_bounds__(512, 2) hymba_fwd(Params p) {
;     ...
;         PSTAMP0(4);
;         if (bx < 128) { sample_outproj(p, lds, bx); __syncthreads(); }
;         PSTAMP0(5);
.LBB0_1219:
	s_cmp_eq_u32 s98, 4
	s_cbranch_scc0 .Lp5_exit
	v_readlane_b32 s0, v254, 4
	s_cmp_lt_i32 s0, 6
	s_cbranch_scc1 .Lp5_exit
	s_cmpk_gt_i32 s95, 0x7f
	s_cbranch_scc1 .Lp5_exit
	s_mov_b32 s98, 5
	v_mov_b32_e32 v0, v255
	s_waitcnt vmcnt(0) lgkmcnt(0)
	s_barrier
	v_cmp_eq_u32_e32 vcc, 0, v0
	s_and_saveexec_b64 s[0:1], vcc
	s_cbranch_execz .Lp5_pe
	s_mov_b32 s5, 0x8000
	v_mov_b32_e32 v2, 0xc00
.Lp5_poll:
	global_load_dword v1, v2, s[90:91] sc1
	s_waitcnt vmcnt(0)
	v_readfirstlane_b32 s4, v1
	s_cmpk_gt_u32 s4, 63
	s_cbranch_scc1 .Lp5_pd
	s_add_i32 s5, s5, -1
	s_cmp_eq_u32 s5, 0
	s_cbranch_scc1 .Lp5_pd
	s_sleep 8
	s_branch .Lp5_poll

; #define LAS __attribute__((address_space(3)))
; #define PSTAMP0(i) do { if (PROBE_SEG >= 40 && blockIdx.x == 0 && threadIdx.x == 0) ((volatile LAS unsigned long long*)(ctlw + 32))[20 + (i)] = __builtin_amdgcn_s_memrealtime(); } while (0)
; __device__ __forceinline__ void sample_outproj(const Params& p, LAS unsigned char* lds, int c) {
;     int tid = threadIdx.x; asm volatile("" : "+v"(tid));
;     const int wid = __builtin_amdgcn_readfirstlane(tid >> 6), lane = tid & 63, j16 = lane & 15, ig = lane >> 4;
;     const bf16_t* MIX = (const bf16_t*)(p.ws + WS_MIX) + (size_t)MP * 2048; const bf16_t* WT = (const bf16_t*)(p.ws + WS_WOUT) + (size_t)(16 * c) * 2048;
; __global__ void __launch_bounds__(512, 2) hymba_fwd(Params p) {
;     ...
;         Epi5 E{p.in[I_XP], p.out, (const float*)(p.ws + WS_SSQ)};
;         PSTAMP0(4);
;         if (bx < 128) { sample_outproj(p, lds, bx); __syncthreads(); }
.Lp5_pe:
	s_or_b64 exec, exec, s[0:1]
	s_barrier
	v_readlane_b32 s2, v254, 0
	v_readlane_b32 s3, v254, 1
	s_sub_u32 s2, s2, 0xe8
	s_subb_u32 s3, s3, 0
	s_load_dwordx2 s[38:39], s[2:3], 0x8
	s_add_u32 s24, s90, 0x2600000
	s_addc_u32 s33, s91, 0
	s_waitcnt lgkmcnt(0)
	s_branch .Lp5_sample
